# NSA selected-block loop: tile list entries carried in scalars and read three steps ahead (was two dependent LDS reads + waits on every step)
# speedup vs baseline: 1.0082x; 1.0082x over previous
; DI void attn_init(AttnState& s) { for (int i = 0; i < 4; ++i) s.o[i] = zero16(); s.m = NEG_INF; s.l = 0.f; }
; DI void nsa_winslc(const Params& p, const NsaCtx c) {
;     ...
;     const int nsteps = __builtin_amdgcn_readfirstlane(tl[159]);
;     attn_init(st);
;     if (nsteps > 0) { const int k0 = __builtin_amdgcn_readfirstlane(tl[0]); kv_issue(stg, KS + (size_t)k0 * 4096, VST + (size_t)k0 * 4096, L); }
;     if (nsteps > 1) { const int k1 = __builtin_amdgcn_readfirstlane(tl[1]); kv_issue(stg + AT_STAGE, KS + (size_t)k1 * 4096, VST + (size_t)k1 * 4096, L); }
; #pragma unroll 1
;     for (int i = 0; i < nsteps; ++i) {
;       const int kt = __builtin_amdgcn_readfirstlane(tl[i]);
.LBB0_261:
	s_andn2_b64 vcc, exec, s[6:7]
	s_cbranch_vccnz .LBB0_198
	v_mov_b32_e32 v16, v1
	v_mov_b32_e32 v17, v1
	v_mov_b32_e32 v2, v1
	v_mov_b32_e32 v3, v1
	v_mov_b32_e32 v4, v1
	v_mov_b32_e32 v5, v1
	v_mov_b32_e32 v6, v1
	v_mov_b32_e32 v7, v1
	v_mov_b32_e32 v8, v1
	v_mov_b32_e32 v9, v1
	v_mov_b32_e32 v10, v1
	v_mov_b32_e32 v11, v1
	v_mov_b32_e32 v12, v1
	v_mov_b32_e32 v13, v1
	v_mov_b32_e32 v14, v1
	v_mov_b32_e32 v15, v1
	v_mov_b64_e32 v[32:33], v[16:17]
	v_mov_b64_e32 v[48:49], v[16:17]
	v_mov_b64_e32 v[64:65], v[16:17]
	v_lshl_add_u64 v[122:123], s[2:3], 0, v[122:123]
	v_lshl_add_u64 v[128:129], s[4:5], 0, v[120:121]
	s_or_b32 s4, s9, 31
	s_sub_i32 s5, s9, 31
	v_mov_b32_e32 v115, v114
	v_or_b32_e32 v117, 0x10000, v130
	v_or_b32_e32 v217, 0x10000, v131
	v_or_b32_e32 v218, 0x10000, v132
	v_or_b32_e32 v219, 0x10000, v133
	v_or_b32_e32 v220, 0x10000, v134
	v_or_b32_e32 v221, 0x10000, v135
	v_or_b32_e32 v222, 0x10000, v136
	v_or_b32_e32 v223, 0x10000, v137
	s_add_i32 s6, s11, 0x18000
	s_add_i32 s11, s11, 0x1a000
	s_mov_b32 s7, 0
	v_mov_b32_e32 v0, 0
	v_mov_b32_e32 v224, 0xff800000
	s_mov_b32 s12, 2
	s_mov_b32 s13, 0
	s_mov_b32 s15, 0
	v_mov_b32_e32 v206, 0x1c000
	ds_read_b32 v206, v206
	s_waitcnt lgkmcnt(0)
	v_readfirstlane_b32 s17, v206
	v_mov_b32_e32 v206, 0x1c004
	ds_read_b32 v206, v206
	s_waitcnt lgkmcnt(0)
	v_readfirstlane_b32 s100, v206
	v_mov_b32_e32 v206, 0x1c008
	ds_read_b32 v206, v206
	s_waitcnt lgkmcnt(0)
	v_readfirstlane_b32 s101, v206
	v_mov_b64_e32 v[30:31], v[14:15]
	v_mov_b64_e32 v[28:29], v[12:13]
	v_mov_b64_e32 v[26:27], v[10:11]
	v_mov_b64_e32 v[24:25], v[8:9]
	v_mov_b64_e32 v[22:23], v[6:7]
	v_mov_b64_e32 v[20:21], v[4:5]
	v_mov_b64_e32 v[18:19], v[2:3]
	v_mov_b64_e32 v[46:47], v[14:15]
	v_mov_b64_e32 v[44:45], v[12:13]
	v_mov_b64_e32 v[42:43], v[10:11]
	v_mov_b64_e32 v[40:41], v[8:9]
	v_mov_b64_e32 v[38:39], v[6:7]
	v_mov_b64_e32 v[36:37], v[4:5]
	v_mov_b64_e32 v[34:35], v[2:3]
	v_mov_b64_e32 v[62:63], v[14:15]
	v_mov_b64_e32 v[60:61], v[12:13]
	v_mov_b64_e32 v[58:59], v[10:11]
	v_mov_b64_e32 v[56:57], v[8:9]
	v_mov_b64_e32 v[54:55], v[6:7]
	v_mov_b64_e32 v[52:53], v[4:5]
	v_mov_b64_e32 v[50:51], v[2:3]
	v_mov_b32_e32 v160, 0
	v_mov_b32_e32 v161, 0
	v_mov_b32_e32 v156, 0
	v_mov_b32_e32 v157, 0
	v_mov_b32_e32 v154, 0
	v_mov_b32_e32 v155, 0
	v_mov_b32_e32 v152, 0
	v_mov_b32_e32 v153, 0
	v_mov_b32_e32 v150, 0
	v_mov_b32_e32 v151, 0
	v_mov_b32_e32 v148, 0
	v_mov_b32_e32 v149, 0
	v_mov_b32_e32 v146, 0
	v_mov_b32_e32 v147, 0
	v_mov_b32_e32 v144, 0
	v_mov_b32_e32 v145, 0
	v_mov_b32_e32 v174, 0
	v_mov_b32_e32 v175, 0
	v_mov_b32_e32 v172, 0
	v_mov_b32_e32 v173, 0
	v_mov_b32_e32 v170, 0
	v_mov_b32_e32 v171, 0
	v_mov_b32_e32 v168, 0
	v_mov_b32_e32 v169, 0
	v_mov_b32_e32 v166, 0
	v_mov_b32_e32 v167, 0
	v_mov_b32_e32 v164, 0
	v_mov_b32_e32 v165, 0
	v_mov_b32_e32 v162, 0
	v_mov_b32_e32 v163, 0
	v_mov_b32_e32 v138, 0
	v_mov_b32_e32 v139, 0
	v_mov_b32_e32 v158, 0
	v_mov_b32_e32 v159, 0
	v_mov_b32_e32 v142, 0
	v_mov_b32_e32 v143, 0
	v_mov_b32_e32 v140, 0
	v_mov_b32_e32 v141, 0
	v_mov_b32_e32 v136, 0
	v_mov_b32_e32 v137, 0
	v_mov_b32_e32 v134, 0
	v_mov_b32_e32 v135, 0
	v_mov_b32_e32 v132, 0
	v_mov_b32_e32 v133, 0
	v_mov_b32_e32 v120, 0
	v_mov_b32_e32 v121, 0
	v_mov_b32_e32 v76, 0
	v_mov_b32_e32 v77, 0
	v_mov_b32_e32 v130, 0
	v_mov_b32_e32 v131, 0
	v_mov_b32_e32 v80, 0
	v_mov_b32_e32 v81, 0
	v_mov_b32_e32 v78, 0
	v_mov_b32_e32 v79, 0
	v_mov_b32_e32 v74, 0
	v_mov_b32_e32 v75, 0
	v_mov_b32_e32 v72, 0
	v_mov_b32_e32 v73, 0
	v_mov_b32_e32 v70, 0
	v_mov_b32_e32 v71, 0
	v_mov_b32_e32 v68, 0
	v_mov_b32_e32 v69, 0
	v_mov_b32_e32 v66, 0
	v_mov_b32_e32 v67, 0
.LBB0_263:
	s_add_i32 s18, s13, 0
	s_add_i32 s14, s15, 1
	s_cmp_ge_i32 s14, s16
	s_mov_b64 s[2:3], -1
	s_cbranch_scc0 .LBB0_265
	s_waitcnt vmcnt(0)
	s_mov_b64 s[2:3], 0

; #define NEG_INF (-__builtin_inff())
; #define LAS __attribute__((address_space(3)))
; #define AT_WAIT_V(n) asm volatile("s_waitcnt vmcnt(" #n ")" ::: "memory")
; #define AT_BAR() __builtin_amdgcn_s_barrier()
; DI void nsa_winslc(const Params& p, const NsaCtx c) {
;     ...
;       const int kt = __builtin_amdgcn_readfirstlane(tl[i]);
;       if (i + 1 < nsteps) AT_WAIT_V(2); else AT_WAIT_V(0);
;       AT_BAR();
;       if (i + 2 < nsteps) { const int k2 = __builtin_amdgcn_readfirstlane(tl[i + 2]); kv_issue(stg + ((i + 2) % 3) * AT_STAGE, KS + (size_t)k2 * 4096, VST + (size_t)k2 * 4096, L); }
;       const int mb = kt >> 1, key0 = kt * 32;
;       if (((uni >> mb) & 1ull) && key0 <= t0 + 31 && t0 - (key0 + 31) <= thr) {
;         const bool mine = (mymask >> mb) & 1ull;
;         const LAS unsigned char* sg = stg + (i % 3) * AT_STAGE;
;         f32x16 acc = score_tile_lds(qf, sg, L);
;         float sc[16];
;         const int d0 = tq - key0 - 4 * g;
;         const float fb = mine ? slope2 * (float)d0 : __builtin_inff();
; #pragma unroll
;         for (int q = 0; q < 16; ++q) sc[q] = fmaf(slope2, (float)((q & 3) + 8 * (q >> 2)), acc[q]) - fb;
;         if (key0 >= t0) {
; #pragma unroll
;           for (int q = 0; q < 16; ++q) sc[q] = (d0 - ((q & 3) + 8 * (q >> 2)) >= 0) ? sc[q] : NEG_INF;
.LBB0_267:
	s_add_i32 s2, s15, 2
	s_cmp_ge_i32 s2, s16
	s_barrier
	s_cbranch_scc1 .LBB0_269
	s_mul_hi_u32 s2, s12, 0xaaaaaaab
	s_lshr_b32 s2, s2, 1
	s_mul_i32 s2, s2, 0xc000
	s_sub_i32 s18, s6, s2
	s_sub_i32 s19, s11, s2
	s_mov_b32 s2, s101
	s_ashr_i32 s3, s2, 31
	s_lshl_b64 s[2:3], s[2:3], 13
	s_add_i32 s18, s7, s18
	v_lshl_add_u64 v[176:177], v[122:123], 0, s[2:3]
	s_add_i32 m0, s18, 0
	s_nop 0
	global_load_lds_dwordx4 v[176:177], off
	v_lshl_add_u64 v[176:177], v[128:129], 0, s[2:3]
	s_add_i32 s2, s7, s19
	s_add_i32 m0, s2, 0
	s_nop 0
	global_load_lds_dwordx4 v[176:177], off
.LBB0_269:
	s_add_i32 s2, s13, 0x1c00c
	v_mov_b32_e32 v206, s2
	ds_read_b32 v206, v206
	s_ashr_i32 s2, s17, 1
	s_lshl_b64 s[2:3], 1, s2
	s_lshl_b32 s17, s17, 5
	s_and_b64 s[18:19], s[2:3], s[0:1]
	s_cmp_eq_u64 s[18:19], 0
	s_cselect_b64 s[18:19], -1, 0
	s_cmp_gt_i32 s17, s4
	s_cselect_b64 s[20:21], -1, 0
	s_sub_i32 s22, s5, s17
	s_cmp_gt_i32 s22, s10
	s_cselect_b64 s[22:23], -1, 0
	s_or_b64 s[20:21], s[20:21], s[22:23]
	s_or_b64 s[18:19], s[20:21], s[18:19]
	s_and_b64 vcc, exec, s[18:19]
	s_cbranch_vccnz .LBB0_275
	s_mul_hi_u32 s15, s15, 0xaaaaaaab
	s_lshr_b32 s15, s15, 1
	s_mul_i32 s15, s15, 0xc000
	v_add_u32_e32 v121, s7, v215
	v_subrev_u32_e32 v186, s15, v223
	v_add_u32_e32 v186, v121, v186
	ds_read_b128 v[186:189], v186
	v_subrev_u32_e32 v194, s15, v222
	v_add_u32_e32 v194, v121, v194
	ds_read_b128 v[194:197], v194
	v_subrev_u32_e32 v200, s15, v221
	v_add_u32_e32 v200, v121, v200
	ds_read_b128 v[200:203], v200
	v_subrev_u32_e32 v228, s15, v220
	v_add_u32_e32 v228, v121, v228
	ds_read_b128 v[228:231], v228
	v_subrev_u32_e32 v232, s15, v219
	v_add_u32_e32 v232, v121, v232
	ds_read_b128 v[232:235], v232
	v_subrev_u32_e32 v236, s15, v218
	v_add_u32_e32 v236, v121, v236
	ds_read_b128 v[236:239], v236
	v_subrev_u32_e32 v240, s15, v217
	v_add_u32_e32 v240, v121, v240
	ds_read_b128 v[240:243], v240
	v_subrev_u32_e32 v244, s15, v117
	v_add_u32_e32 v244, v121, v244
	ds_read_b128 v[244:247], v244
	s_cmp_lt_i32 s17, s9
	v_or_b32_e32 v120, s17, v180
	v_sub_u32_e32 v120, v116, v120
	v_cvt_f32_i32_e32 v121, v120
	v_mul_f32_e32 v121, v114, v121
	v_and_b32_e32 v131, s3, v119
	v_and_b32_e32 v130, s2, v118
	s_mov_b32 s2, 2.0
	s_mov_b32 s3, 0x40400000
	v_cmp_ne_u64_e32 vcc, 0, v[130:131]
	v_mov_b32_e32 v130, 0x7f800000
	s_waitcnt lgkmcnt(7)
	v_mfma_f32_32x32x16_bf16 v[66:81], v[186:189], v[82:85], 0
	s_waitcnt lgkmcnt(6)
	v_mfma_f32_32x32x16_bf16 v[66:81], v[194:197], v[86:89], v[66:81]
	s_waitcnt lgkmcnt(5)
	v_mfma_f32_32x32x16_bf16 v[66:81], v[200:203], v[90:93], v[66:81]
	s_waitcnt lgkmcnt(4)
	v_mfma_f32_32x32x16_bf16 v[66:81], v[228:231], v[94:97], v[66:81]
	s_waitcnt lgkmcnt(3)
	v_mfma_f32_32x32x16_bf16 v[66:81], v[232:235], v[98:101], v[66:81]
	s_waitcnt lgkmcnt(2)
	v_mfma_f32_32x32x16_bf16 v[66:81], v[236:239], v[102:105], v[66:81]
	s_waitcnt lgkmcnt(1)
	v_mfma_f32_32x32x16_bf16 v[66:81], v[240:243], v[106:109], v[66:81]
	s_waitcnt lgkmcnt(0)
	v_mfma_f32_32x32x16_bf16 v[66:81], v[244:247], v[110:113], v[66:81]
	v_cndmask_b32_e32 v130, v130, v121, vcc
	v_add_u32_e32 v190, s7, v181
	v_subrev_u32_e32 v186, s15, v214
	v_add_u32_e32 v186, v190, v186
	ds_read_b64 v[186:187], v186
	v_subrev_u32_e32 v188, s15, v211
	v_add_u32_e32 v188, v190, v188
	ds_read_b64 v[188:189], v188
	v_subrev_u32_e32 v194, s15, v213
	v_add_u32_e32 v194, v190, v194
	ds_read_b64 v[194:195], v194
	v_subrev_u32_e32 v196, s15, v210
	v_add_u32_e32 v196, v190, v196
	ds_read_b64 v[196:197], v196
	v_subrev_u32_e32 v200, s15, v208
	v_add_u32_e32 v200, v190, v200
	ds_read_b64 v[200:201], v200
	v_subrev_u32_e32 v202, s15, v184
	v_add_u32_e32 v202, v190, v202
	ds_read_b64 v[202:203], v202
	v_subrev_u32_e32 v228, s15, v207
	v_add_u32_e32 v228, v190, v228
	ds_read_b64 v[228:229], v228
	v_subrev_u32_e32 v230, s15, v183
	v_add_u32_e32 v230, v190, v230
	ds_read_b64 v[230:231], v230
	v_subrev_u32_e32 v232, s15, v212
	v_add_u32_e32 v232, v190, v232
	ds_read_b64 v[236:237], v232 offset:2048
	ds_read_b64 v[232:233], v232
	v_subrev_u32_e32 v234, s15, v209
	v_add_u32_e32 v234, v190, v234
	ds_read_b64 v[238:239], v234 offset:2048
	ds_read_b64 v[234:235], v234
	v_pk_fma_f32 v[68:69], v[114:115], s[2:3], v[68:69]
	s_mov_b32 s2, 0x41000000
	s_mov_b32 s3, 0x41100000
	v_pk_fma_f32 v[70:71], v[114:115], s[2:3], v[70:71]
	s_mov_b32 s2, 0x41200000
	s_mov_b32 s3, 0x41300000
	v_pk_fma_f32 v[72:73], v[114:115], s[2:3], v[72:73]
	s_mov_b32 s2, 0x41800000
	s_mov_b32 s3, 0x41880000
	v_pk_fma_f32 v[132:133], v[114:115], s[2:3], v[74:75]
	s_mov_b32 s2, 0x41900000
	s_mov_b32 s3, 0x41980000
	v_pk_fma_f32 v[134:135], v[114:115], s[2:3], v[76:77]
	s_mov_b32 s2, 0x41c00000
	s_mov_b32 s3, 0x41c80000
	v_pk_fma_f32 v[136:137], v[114:115], s[2:3], v[78:79]
	s_mov_b32 s2, 0x41d00000
	s_mov_b32 s3, 0x41d80000
	v_fma_f32 v66, 0, v114, v66
	v_add_f32_e32 v67, v114, v67
	v_pk_fma_f32 v[138:139], v[114:115], s[2:3], v[80:81]
	v_pk_add_f32 v[80:81], v[66:67], v[130:131] op_sel_hi:[1,0] neg_lo:[0,1] neg_hi:[0,1]
	v_pk_add_f32 v[78:79], v[68:69], v[130:131] op_sel_hi:[1,0] neg_lo:[0,1] neg_hi:[0,1]
	v_pk_add_f32 v[76:77], v[70:71], v[130:131] op_sel_hi:[1,0] neg_lo:[0,1] neg_hi:[0,1]
	v_pk_add_f32 v[74:75], v[72:73], v[130:131] op_sel_hi:[1,0] neg_lo:[0,1] neg_hi:[0,1]
	v_pk_add_f32 v[72:73], v[132:133], v[130:131] op_sel_hi:[1,0] neg_lo:[0,1] neg_hi:[0,1]
	v_pk_add_f32 v[70:71], v[134:135], v[130:131] op_sel_hi:[1,0] neg_lo:[0,1] neg_hi:[0,1]
	v_pk_add_f32 v[68:69], v[136:137], v[130:131] op_sel_hi:[1,0] neg_lo:[0,1] neg_hi:[0,1]
	v_pk_add_f32 v[66:67], v[138:139], v[130:131] op_sel_hi:[1,0] neg_lo:[0,1] neg_hi:[0,1]
	s_cbranch_scc1 .LBB0_272
	v_cmp_lt_i32_e32 vcc, 0, v120
	s_nop 1
	v_cndmask_b32_e32 v81, v248, v81, vcc
	v_cmp_lt_i32_e32 vcc, -1, v120
	s_nop 1
	v_cndmask_b32_e32 v80, v248, v80, vcc
	v_cmp_lt_i32_e32 vcc, 2, v120
	s_nop 1
	v_cndmask_b32_e32 v79, v248, v79, vcc
	v_cmp_lt_i32_e32 vcc, 1, v120
	s_nop 1
	v_cndmask_b32_e32 v78, v248, v78, vcc
	v_cmp_lt_i32_e32 vcc, 8, v120
	s_nop 1
	v_cndmask_b32_e32 v77, v248, v77, vcc
	v_cmp_lt_i32_e32 vcc, 7, v120
	s_nop 1
	v_cndmask_b32_e32 v76, v248, v76, vcc
	v_cmp_lt_i32_e32 vcc, 10, v120
	s_nop 1
	v_cndmask_b32_e32 v75, v248, v75, vcc
	v_cmp_lt_i32_e32 vcc, 9, v120
	s_nop 1
	v_cndmask_b32_e32 v74, v248, v74, vcc
	v_cmp_lt_i32_e32 vcc, 16, v120
	s_nop 1
	v_cndmask_b32_e32 v73, v248, v73, vcc
	v_cmp_lt_i32_e32 vcc, 15, v120
	s_nop 1
	v_cndmask_b32_e32 v72, v248, v72, vcc
	v_cmp_lt_i32_e32 vcc, 18, v120
	s_nop 1
	v_cndmask_b32_e32 v71, v248, v71, vcc
	v_cmp_lt_i32_e32 vcc, 17, v120
	s_nop 1
	v_cndmask_b32_e32 v70, v248, v70, vcc
	v_cmp_lt_i32_e32 vcc, 24, v120
	s_nop 1
	v_cndmask_b32_e32 v69, v248, v69, vcc
	v_cmp_lt_i32_e32 vcc, 23, v120
	s_nop 1
	v_cndmask_b32_e32 v68, v248, v68, vcc
	v_cmp_lt_i32_e32 vcc, 26, v120
	s_nop 1
	v_cndmask_b32_e32 v67, v248, v67, vcc
	v_cmp_lt_i32_e32 vcc, 25, v120
	s_nop 1
	v_cndmask_b32_e32 v66, v248, v66, vcc

; #define AT_WAIT_V(n) asm volatile("s_waitcnt vmcnt(" #n ")" ::: "memory")
; #define AT_BAR() __builtin_amdgcn_s_barrier()
; DI void nsa_winslc(const Params& p, const NsaCtx c) {
;     ...
; #pragma unroll 1
;     for (int i = 0; i < nsteps; ++i) {
;       const int kt = __builtin_amdgcn_readfirstlane(tl[i]);
;       if (i + 1 < nsteps) AT_WAIT_V(2); else AT_WAIT_V(0);
;       AT_BAR();
;       if (i + 2 < nsteps) { const int k2 = __builtin_amdgcn_readfirstlane(tl[i + 2]); kv_issue(stg + ((i + 2) % 3) * AT_STAGE, KS + (size_t)k2 * 4096, VST + (size_t)k2 * 4096, L); }
.LBB0_276:
	s_waitcnt lgkmcnt(0)
	v_readfirstlane_b32 s2, v206
	s_mov_b32 s17, s100
	s_mov_b32 s100, s101
	s_nop 0
	s_mov_b32 s101, s2
	s_add_i32 s13, s13, 4
	s_addk_i32 s7, 0x4000
	s_add_i32 s12, s12, 1
	s_cmp_eq_u32 s16, s14
	s_cbranch_scc1 .Lsel_exit
	s_mov_b32 s15, s14
	v_mov_b32_e32 v224, v225
	s_branch .LBB0_263
